# FF1 epilogue: next unit's per-row sum-of-squares partials prefetched into LDS by LDS-DMA during the current epilogue (double-buffered); the per-unit global-load round trip at the top of the epilogue i
# speedup vs baseline: 1.0053x; 1.0053x over previous
;     __device__ bool next(int i, Unit& u) const { const long L = (long)i * G + c; if (L >= 128) return false; u.pm = (int)L & 31; u.pn = u.pm >> 4; u.koff = ((int)L >> 5) * 1024; return true; }
;     __host__ __device__ bool next(int i, Unit& u) const {
;         const long L = (long)i * G + c; if (L >= nwg) return false;
;         int wgid = (int)L; { const int q = nwg / NXCD, r = nwg % NXCD, xcd = wgid % NXCD, off = wgid / NXCD; wgid = (xcd < r ? xcd * (q + 1) : r * (q + 1) + (xcd - r) * q) + off; }
;         const int nig = WGM * nN, gid = wgid / nig, fm = gid * WGM, gsz = (nM - fm) < WGM ? (nM - fm) : WGM;
;         u.pm = fm + ((wgid % nig) % gsz); u.pn = (wgid % nig) / gsz; u.koff = 0; return true;
; __global__ void __launch_bounds__(NWAVES * 64, 2) fwd_kernel(Args args) {
;     ...
;     if (IN(6)) {
;         pg8::Gemm g{(const bf16_t*)(ws + WS_X2B), (const bf16_t*)(ws + WS_WFF1), T, FF, DM, DM, DM};
;         pg8::StaticOrder So; So.init(T, FF, G, (int)blockIdx.x);
;         EpiFF1 E{(const float*)(ws + WS_SSQP), (bf16_t*)(ws + WS_H)};
;         pg8::gemm_phase<EpiFF1, pg8::StaticOrder, true, true>(lds, g, So, E);
.LBB0_989:
	s_mov_b32 s84, 0
	s_mov_b32 s85, 0
	s_mov_b32 s98, 0
	s_add_u32 s100, s78, 0x12f00
	s_addc_u32 s101, s79, 0
	v_readlane_b32 s0, v254, 0
	v_readlane_b32 s1, v254, 1
	s_cmp_lt_i32 s0, 7
	s_cselect_b64 s[0:1], -1, 0
	s_and_b64 s[0:1], s[0:1], s[72:73]
	s_andn2_b64 vcc, exec, s[0:1]
	s_cbranch_vccnz .LBB0_1014
	s_cmpk_gt_i32 s70, 0x7ff
	v_readfirstlane_b32 s4, v184
	s_cbranch_scc1 .LBB0_1014
	s_ashr_i32 s14, s70, 31
	s_lshr_b32 s2, s14, 29
	s_add_i32 s7, s70, s2
	s_and_b32 s2, s7, -8
	s_sub_i32 s6, s70, s2
	s_cmp_gt_i32 s6, -1
	s_cbranch_scc0 .LBB0_993
	s_lshl_b32 s5, s6, 8
	s_ashr_i32 s2, s7, 3
	s_cbranch_execz .LBB0_994
	s_branch .LBB0_995

;     __device__ __forceinline__ void operator()(const f32x4 (&acc)[2][2][4][2], const pg8::Unit& u, int wr, int wc, int fr, int fq) const {
;         f32x4 sq[2][4];
; #pragma unroll
;         for (int ai = 0; ai < 2; ++ai)
; #pragma unroll
;             for (int m = 0; m < 4; ++m) sq[ai][m] = *(const f32x4*)(ssqp + (size_t)(u.pm * 256 + ai * 128 + wr * 64 + m * 16 + fr) * 4);
;         __builtin_amdgcn_sched_barrier(0);
.Lh_ok:
	s_cmp_eq_u32 s85, 0
	s_cbranch_scc1 .Lr6_glob
	v_lshl_add_u32 v166, s30, 8, v174
	v_or_b32_e32 v198, 16, v166
	v_ashrrev_i32_e32 v167, 31, v166
	v_ashrrev_i32_e32 v199, 31, v198
	v_or_b32_e32 v200, 32, v166
	v_or_b32_e32 v172, 48, v166
	v_lshl_add_u64 v[128:129], v[166:167], 4, s[8:9]
	v_lshl_add_u64 v[130:131], v[198:199], 4, s[8:9]
	v_ashrrev_i32_e32 v201, 31, v200
	v_ashrrev_i32_e32 v173, 31, v172
	v_add_u32_e32 v170, 0x80, v166
	v_add_u32_e32 v168, 0x90, v166
	v_lshl_add_u64 v[128:129], v[200:201], 4, s[8:9]
	v_lshl_add_u64 v[130:131], v[172:173], 4, s[8:9]
	v_ashrrev_i32_e32 v171, 31, v170
	v_ashrrev_i32_e32 v169, 31, v168
	v_add_u32_e32 v164, 0xa0, v166
	v_add_u32_e32 v162, 0xb0, v166
	v_lshl_add_u64 v[128:129], v[170:171], 4, s[8:9]
	v_lshl_add_u64 v[130:131], v[168:169], 4, s[8:9]
	v_ashrrev_i32_e32 v165, 31, v164
	v_ashrrev_i32_e32 v163, 31, v162
	v_lshl_add_u64 v[128:129], v[164:165], 4, s[8:9]
	v_lshl_add_u64 v[130:131], v[162:163], 4, s[8:9]
	s_nop 0
	v_lshlrev_b64 v[166:167], 13, v[166:167]
	v_lshlrev_b32_e32 v218, 4, v174
	v_add_u32_e32 v218, s84, v218
	v_add_u32_e32 v218, 0x20000, v218
	ds_read_b128 v[180:183], v218
	ds_read_b128 v[186:189], v218 offset:256
	ds_read_b128 v[190:193], v218 offset:512
	ds_read_b128 v[194:197], v218 offset:768
	ds_read_b128 v[140:143], v218 offset:2048
	ds_read_b128 v[136:139], v218 offset:2304
	ds_read_b128 v[132:135], v218 offset:2560
	ds_read_b128 v[128:131], v218 offset:2816
	s_waitcnt lgkmcnt(0)
	s_branch .Lr6_join

;     __device__ __forceinline__ void operator()(const f32x4 (&acc)[2][2][4][2], const pg8::Unit& u, int wr, int wc, int fr, int fq) const {
;         f32x4 sq[2][4];
; #pragma unroll
;         for (int ai = 0; ai < 2; ++ai)
; #pragma unroll
;             for (int m = 0; m < 4; ++m) sq[ai][m] = *(const f32x4*)(ssqp + (size_t)(u.pm * 256 + ai * 128 + wr * 64 + m * 16 + fr) * 4);
;         __builtin_amdgcn_sched_barrier(0);
; #pragma unroll
;         for (int ai = 0; ai < 2; ++ai)
; #pragma unroll
;             for (int m = 0; m < 4; ++m) {
;                 const int row = u.pm * 256 + ai * 128 + wr * 64 + m * 16 + fr;
;                 const float tot = (sq[ai][m].x + sq[ai][m].y) + (sq[ai][m].z + sq[ai][m].w);
;                 const float rn = rsqrtf(tot * (1.f / 1024.f) + EPS);
; #pragma unroll
;                 for (int bj = 0; bj < 2; ++bj) {
;                     float y[8];
; #pragma unroll
;                     for (int n = 0; n < 2; ++n)
; #pragma unroll
;                         for (int e = 0; e < 4; ++e) { const float h = fmaxf(acc[ai][bj][m][n][e] * rn, 0.f); y[n * 4 + e] = h * h; }
;                     store8(H + (size_t)row * FF + u.pn * 256 + 128 * bj + 32 * wc + 8 * fq, y);
;                 }
.Lr6_join:
	s_xor_b32 s84, s84, 0x1000
	s_mov_b32 s85, 1
	s_cmp_lg_u64 s[2:3], 0
	s_cbranch_scc0 .Lr6_nodma
	v_readfirstlane_b32 s82, v184
	s_lshr_b32 s82, s82, 6
	s_cmp_gt_u32 s82, 3
	s_cbranch_scc1 .Lr6_nodma
	s_lshl_b32 s83, s24, 8
	s_lshl_b32 s81, s82, 6
	s_add_i32 s83, s83, s81
	v_and_b32_e32 v218, 63, v184
	v_add_u32_e32 v218, s83, v218
	v_lshlrev_b32_e32 v218, 4, v218
	s_lshl_b32 s82, s82, 10
	s_add_i32 s82, s82, s84
	s_add_i32 m0, s82, 0x20000
	s_nop 1
	global_load_lds_dwordx4 v218, s[8:9]
.Lr6_nodma:
	v_mov_b32_e32 v202, v181
	v_mov_b32_e32 v203, v182
	v_mov_b32_e32 v181, v183
	v_lshl_add_u64 v[182:183], s[10:11], 0, v[166:167]
	v_mov_b32_e32 v166, v187
	v_mov_b32_e32 v167, v188
	v_mov_b32_e32 v187, v189
	v_pk_add_f32 v[180:181], v[202:203], v[180:181]
	v_pk_add_f32 v[166:167], v[166:167], v[186:187]
	v_mov_b32_e32 v187, v180
	v_mov_b32_e32 v186, v166
	v_mov_b32_e32 v180, v167
	v_pk_add_f32 v[180:181], v[186:187], v[180:181]
	v_mov_b64_e32 v[166:167], s[20:21]
	v_pk_fma_f32 v[180:181], v[180:181], s[18:19], v[166:167] op_sel_hi:[1,0,0]
	s_lshl_b32 s30, s31, 8
	v_mul_f32_e32 v179, 0x4b800000, v181
	v_cmp_gt_f32_e32 vcc, s50, v181
	s_ashr_i32 s31, s30, 31
	s_lshl_b64 s[30:31], s[30:31], 1
	v_cndmask_b32_e32 v179, v181, v179, vcc
	v_rsq_f32_e32 v179, v179
	v_lshl_add_u64 v[182:183], v[182:183], 0, s[30:31]
	v_lshl_add_u64 v[182:183], v[182:183], 0, s[4:5]
	v_lshl_add_u64 v[182:183], v[182:183], 0, v[152:153]
	v_mul_f32_e32 v181, 0x45800000, v179
	v_cndmask_b32_e32 v179, v179, v181, vcc
	v_mul_f32_e32 v120, v120, v179
	v_max_f32_e32 v120, 0, v120
	v_mul_f32_e32 v181, v120, v120
	v_mul_f32_e32 v120, v121, v179
	v_max_f32_e32 v120, 0, v120
	v_mul_f32_e32 v185, v120, v120
	v_mul_f32_e32 v120, v122, v179
	v_max_f32_e32 v120, 0, v120
	v_mul_f32_e32 v124, v124, v179
	v_mul_f32_e32 v125, v125, v179
	v_mul_f32_e32 v186, v120, v120
	v_mul_f32_e32 v120, v123, v179
	v_max_f32_e32 v124, 0, v124
	v_max_f32_e32 v125, 0, v125
	v_mul_f32_e32 v126, v126, v179
	v_mul_f32_e32 v127, v127, v179
	v_max_f32_e32 v120, 0, v120
	v_mul_f32_e32 v112, v112, v179
	v_mul_f32_e32 v124, v124, v124
	v_mul_f32_e32 v125, v125, v125
	v_max_f32_e32 v126, 0, v126
	v_max_f32_e32 v127, 0, v127
	v_mul_f32_e32 v123, v120, v120
	v_cvt_pk_bf16_f32 v120, v124, v125
	v_max_f32_e32 v112, 0, v112
	v_mul_f32_e32 v126, v126, v126
	v_mul_f32_e32 v127, v127, v127
	v_cvt_pk_bf16_f32 v121, v126, v127
	v_cvt_pk_bf16_f32 v122, v181, v185
	v_cvt_pk_bf16_f32 v123, v186, v123
	global_store_dwordx4 v[182:183], v[120:123], off nt
	v_mul_f32_e32 v116, v116, v179
	v_max_f32_e32 v116, 0, v116
	v_mul_f32_e32 v120, v112, v112
	v_mul_f32_e32 v112, v113, v179
	v_max_f32_e32 v112, 0, v112
	v_mul_f32_e32 v121, v112, v112
	v_mul_f32_e32 v112, v114, v179
	v_max_f32_e32 v112, 0, v112
	v_mul_f32_e32 v117, v117, v179
	v_mul_f32_e32 v122, v112, v112
	v_mul_f32_e32 v112, v115, v179
	v_mul_f32_e32 v114, 0x4b800000, v180
	v_cmp_gt_f32_e32 vcc, s50, v180
	v_mul_f32_e32 v116, v116, v116
	v_max_f32_e32 v117, 0, v117
	v_max_f32_e32 v112, 0, v112
	v_cndmask_b32_e32 v114, v180, v114, vcc
	v_mul_f32_e32 v117, v117, v117
	v_mul_f32_e32 v115, v112, v112
	v_cvt_pk_bf16_f32 v112, v116, v117
	v_rsq_f32_e32 v116, v114
	v_mul_f32_e32 v118, v118, v179
	v_mul_f32_e32 v119, v119, v179
	v_max_f32_e32 v118, 0, v118
	v_max_f32_e32 v119, 0, v119
	v_mul_f32_e32 v118, v118, v118
	v_mul_f32_e32 v119, v119, v119
	v_cvt_pk_bf16_f32 v113, v118, v119
	v_cvt_pk_bf16_f32 v114, v120, v121
	v_cvt_pk_bf16_f32 v115, v122, v115
	global_store_dwordx4 v[182:183], v[112:115], off offset:256 nt
	s_nop 1
	v_mul_f32_e32 v112, 0x45800000, v116
	v_cndmask_b32_e32 v114, v116, v112, vcc
	v_mul_f32_e32 v104, v104, v114
	v_max_f32_e32 v104, 0, v104
	v_mul_f32_e32 v117, v104, v104
	v_mul_f32_e32 v104, v105, v114
	v_mul_f32_e32 v108, v108, v114
	v_max_f32_e32 v104, 0, v104
	v_max_f32_e32 v108, 0, v108
	v_mul_f32_e32 v118, v104, v104
	v_mul_f32_e32 v104, v106, v114
	v_mul_f32_e32 v115, v108, v108
	v_mul_f32_e32 v108, v109, v114
	v_max_f32_e32 v104, 0, v104
	v_max_f32_e32 v108, 0, v108
	v_mul_f32_e32 v119, v104, v104
	v_mul_f32_e32 v104, v107, v114
	v_lshlrev_b64 v[112:113], 13, v[198:199]
	v_mul_f32_e32 v116, v108, v108
	v_mul_f32_e32 v108, v110, v114
	v_max_f32_e32 v104, 0, v104
	v_max_f32_e32 v108, 0, v108
	v_mul_f32_e32 v107, v104, v104
	v_lshl_add_u64 v[104:105], s[10:11], 0, v[112:113]
	v_mul_f32_e32 v110, v108, v108
	v_mul_f32_e32 v108, v111, v114
	v_lshl_add_u64 v[104:105], v[104:105], 0, s[30:31]
	v_max_f32_e32 v108, 0, v108
	v_lshl_add_u64 v[104:105], v[104:105], 0, s[4:5]
	v_mul_f32_e32 v96, v96, v114
	v_mul_f32_e32 v111, v108, v108
	v_lshl_add_u64 v[108:109], v[104:105], 0, v[152:153]
	v_cvt_pk_bf16_f32 v104, v115, v116
	v_max_f32_e32 v96, 0, v96
	v_cvt_pk_bf16_f32 v105, v110, v111
	v_cvt_pk_bf16_f32 v106, v117, v118
	v_cvt_pk_bf16_f32 v107, v119, v107
	global_store_dwordx4 v[108:109], v[104:107], off nt
	v_mul_f32_e32 v100, v100, v114
	v_mul_f32_e32 v101, v101, v114
	v_mul_f32_e32 v104, v96, v96
	v_mul_f32_e32 v96, v97, v114
	v_max_f32_e32 v96, 0, v96
	v_mul_f32_e32 v105, v96, v96
	v_mul_f32_e32 v96, v98, v114
	v_max_f32_e32 v96, 0, v96
	v_mul_f32_e32 v102, v102, v114
	v_mul_f32_e32 v103, v103, v114
	v_mul_f32_e32 v106, v96, v96
	v_mul_f32_e32 v96, v99, v114
	v_max_f32_e32 v100, 0, v100
	v_max_f32_e32 v101, 0, v101
	v_max_f32_e32 v102, 0, v102
	v_max_f32_e32 v103, 0, v103
	v_max_f32_e32 v96, 0, v96
	v_mul_f32_e32 v100, v100, v100
	v_mul_f32_e32 v101, v101, v101
	v_mul_f32_e32 v102, v102, v102
	v_mul_f32_e32 v103, v103, v103
	v_mul_f32_e32 v99, v96, v96
	v_cvt_pk_bf16_f32 v96, v100, v101
	v_cvt_pk_bf16_f32 v97, v102, v103
	v_cvt_pk_bf16_f32 v98, v104, v105
;     __device__ __forceinline__ void operator()(const f32x4 (&acc)[2][2][4][2], const pg8::Unit& u, int wr, int wc, int fr, int fq) const {
;     ...
;         for (int ai = 0; ai < 2; ++ai)
; #pragma unroll
;             for (int m = 0; m < 4; ++m) {
;                 const int row = u.pm * 256 + ai * 128 + wr * 64 + m * 16 + fr;
;                 const float tot = (sq[ai][m].x + sq[ai][m].y) + (sq[ai][m].z + sq[ai][m].w);
;                 const float rn = rsqrtf(tot * (1.f / 1024.f) + EPS);
; #pragma unroll
;                 for (int bj = 0; bj < 2; ++bj) {
;                     float y[8];
; #pragma unroll
;                     for (int n = 0; n < 2; ++n)
; #pragma unroll
;                         for (int e = 0; e < 4; ++e) { const float h = fmaxf(acc[ai][bj][m][n][e] * rn, 0.f); y[n * 4 + e] = h * h; }
;                     store8(H + (size_t)row * FF + u.pn * 256 + 128 * bj + 32 * wc + 8 * fq, y);
;                 }
	v_cvt_pk_bf16_f32 v99, v106, v99
	global_store_dwordx4 v[108:109], v[96:99], off offset:256 nt
	v_mov_b32_e32 v100, v195
	v_mov_b32_e32 v101, v196
	v_mov_b32_e32 v96, v191
	v_mov_b32_e32 v97, v192
	v_mov_b32_e32 v191, v193
	v_mov_b32_e32 v195, v197
	v_pk_add_f32 v[96:97], v[96:97], v[190:191]
	v_pk_add_f32 v[100:101], v[100:101], v[194:195]
	v_mov_b32_e32 v103, v96
	v_mov_b32_e32 v102, v100
	v_mov_b32_e32 v96, v101
	v_pk_add_f32 v[96:97], v[102:103], v[96:97]
	v_lshlrev_b64 v[98:99], 13, v[200:201]
	v_pk_fma_f32 v[96:97], v[96:97], s[18:19], v[166:167] op_sel_hi:[1,0,0]
	v_lshl_add_u64 v[98:99], s[10:11], 0, v[98:99]
	v_mul_f32_e32 v100, 0x4b800000, v97
	v_cmp_gt_f32_e32 vcc, s50, v97
	v_lshl_add_u64 v[98:99], v[98:99], 0, s[30:31]
	v_lshl_add_u64 v[98:99], v[98:99], 0, s[4:5]
	v_cndmask_b32_e32 v97, v97, v100, vcc
	v_rsq_f32_e32 v97, v97
	v_lshl_add_u64 v[98:99], v[98:99], 0, v[152:153]
	v_mul_f32_e32 v100, 0x45800000, v97
	v_cndmask_b32_e32 v97, v97, v100, vcc
	v_mul_f32_e32 v88, v88, v97
	v_max_f32_e32 v88, 0, v88
	v_mul_f32_e32 v100, v88, v88
	v_mul_f32_e32 v88, v89, v97
	v_max_f32_e32 v88, 0, v88
	v_mul_f32_e32 v101, v88, v88
	v_mul_f32_e32 v88, v90, v97
	v_max_f32_e32 v88, 0, v88
	v_mul_f32_e32 v92, v92, v97
	v_mul_f32_e32 v93, v93, v97
	v_mul_f32_e32 v102, v88, v88
	v_mul_f32_e32 v88, v91, v97
	v_max_f32_e32 v92, 0, v92
	v_max_f32_e32 v93, 0, v93
	v_mul_f32_e32 v94, v94, v97
	v_mul_f32_e32 v95, v95, v97
	v_max_f32_e32 v88, 0, v88
	v_mul_f32_e32 v80, v80, v97
	v_mul_f32_e32 v92, v92, v92
	v_mul_f32_e32 v93, v93, v93
	v_max_f32_e32 v94, 0, v94
	v_max_f32_e32 v95, 0, v95
	v_mul_f32_e32 v91, v88, v88
	v_cvt_pk_bf16_f32 v88, v92, v93
	v_max_f32_e32 v80, 0, v80
	v_mul_f32_e32 v94, v94, v94
	v_mul_f32_e32 v95, v95, v95
	v_cvt_pk_bf16_f32 v89, v94, v95
	v_cvt_pk_bf16_f32 v90, v100, v101
	v_cvt_pk_bf16_f32 v91, v102, v91
	global_store_dwordx4 v[98:99], v[88:91], off nt
	v_mul_f32_e32 v84, v84, v97
	v_max_f32_e32 v84, 0, v84
	v_mul_f32_e32 v88, v80, v80
	v_mul_f32_e32 v80, v81, v97
	v_max_f32_e32 v80, 0, v80
	v_mul_f32_e32 v89, v80, v80
	v_mul_f32_e32 v80, v82, v97
	v_max_f32_e32 v80, 0, v80
	v_mul_f32_e32 v85, v85, v97
	v_mul_f32_e32 v90, v80, v80
	v_mul_f32_e32 v80, v83, v97
	v_mul_f32_e32 v82, 0x4b800000, v96
	v_cmp_gt_f32_e32 vcc, s50, v96
	v_mul_f32_e32 v84, v84, v84
	v_max_f32_e32 v85, 0, v85
	v_max_f32_e32 v80, 0, v80
	v_cndmask_b32_e32 v82, v96, v82, vcc
	v_mul_f32_e32 v85, v85, v85
	v_mul_f32_e32 v83, v80, v80
	v_cvt_pk_bf16_f32 v80, v84, v85
	v_rsq_f32_e32 v84, v82
	v_mul_f32_e32 v86, v86, v97
	v_mul_f32_e32 v87, v87, v97
	v_max_f32_e32 v86, 0, v86
	v_max_f32_e32 v87, 0, v87
	v_mul_f32_e32 v86, v86, v86
	v_mul_f32_e32 v87, v87, v87
	v_cvt_pk_bf16_f32 v81, v86, v87
	v_cvt_pk_bf16_f32 v82, v88, v89
	v_cvt_pk_bf16_f32 v83, v90, v83
	global_store_dwordx4 v[98:99], v[80:83], off offset:256 nt
	s_nop 1
	v_mul_f32_e32 v80, 0x45800000, v84
	v_cndmask_b32_e32 v82, v84, v80, vcc
	v_mul_f32_e32 v72, v72, v82
	v_max_f32_e32 v72, 0, v72
	v_mul_f32_e32 v85, v72, v72
	v_mul_f32_e32 v72, v73, v82
	v_mul_f32_e32 v76, v76, v82
	v_max_f32_e32 v72, 0, v72
	v_max_f32_e32 v76, 0, v76
	v_mul_f32_e32 v86, v72, v72
	v_mul_f32_e32 v72, v74, v82
	v_mul_f32_e32 v83, v76, v76
	v_mul_f32_e32 v76, v77, v82
	v_max_f32_e32 v72, 0, v72
	v_max_f32_e32 v76, 0, v76
	v_mul_f32_e32 v87, v72, v72
	v_mul_f32_e32 v72, v75, v82
	v_lshlrev_b64 v[80:81], 13, v[172:173]
	v_mul_f32_e32 v84, v76, v76
	v_mul_f32_e32 v76, v78, v82
	v_max_f32_e32 v72, 0, v72
	v_max_f32_e32 v76, 0, v76
	v_mul_f32_e32 v75, v72, v72
	v_lshl_add_u64 v[72:73], s[10:11], 0, v[80:81]
	v_mul_f32_e32 v78, v76, v76
	v_mul_f32_e32 v76, v79, v82
	v_lshl_add_u64 v[72:73], v[72:73], 0, s[30:31]
	v_max_f32_e32 v76, 0, v76
	v_lshl_add_u64 v[72:73], v[72:73], 0, s[4:5]
	v_mul_f32_e32 v64, v64, v82
	v_mul_f32_e32 v79, v76, v76
	v_lshl_add_u64 v[76:77], v[72:73], 0, v[152:153]
	v_cvt_pk_bf16_f32 v72, v83, v84
	v_max_f32_e32 v64, 0, v64
	v_cvt_pk_bf16_f32 v73, v78, v79
	v_cvt_pk_bf16_f32 v74, v85, v86
	v_cvt_pk_bf16_f32 v75, v87, v75
	global_store_dwordx4 v[76:77], v[72:75], off nt
	v_mul_f32_e32 v68, v68, v82
	v_mul_f32_e32 v69, v69, v82
	v_mul_f32_e32 v72, v64, v64
	v_mul_f32_e32 v64, v65, v82
	v_max_f32_e32 v64, 0, v64
	v_mul_f32_e32 v73, v64, v64
	v_mul_f32_e32 v64, v66, v82
	v_max_f32_e32 v64, 0, v64
	v_mul_f32_e32 v70, v70, v82
	v_mul_f32_e32 v71, v71, v82
	v_mul_f32_e32 v74, v64, v64
	v_mul_f32_e32 v64, v67, v82
	v_max_f32_e32 v68, 0, v68
	v_max_f32_e32 v69, 0, v69
	v_max_f32_e32 v70, 0, v70
	v_max_f32_e32 v71, 0, v71
	v_max_f32_e32 v64, 0, v64
	v_mul_f32_e32 v68, v68, v68
	v_mul_f32_e32 v69, v69, v69
	v_mul_f32_e32 v70, v70, v70
	v_mul_f32_e32 v71, v71, v71
	v_mul_f32_e32 v67, v64, v64
	v_cvt_pk_bf16_f32 v64, v68, v69
	v_cvt_pk_bf16_f32 v65, v70, v71
	v_cvt_pk_bf16_f32 v66, v72, v73
	v_cvt_pk_bf16_f32 v67, v74, v67
	global_store_dwordx4 v[76:77], v[64:67], off offset:256 nt
	v_mov_b32_e32 v68, v137
	v_mov_b32_e32 v69, v138
	v_mov_b32_e32 v64, v141
	v_mov_b32_e32 v65, v142
	v_mov_b32_e32 v141, v143
	v_mov_b32_e32 v137, v139
	v_pk_add_f32 v[64:65], v[64:65], v[140:141]
	v_pk_add_f32 v[68:69], v[68:69], v[136:137]
	v_mov_b32_e32 v71, v64
	v_mov_b32_e32 v70, v68
	v_mov_b32_e32 v64, v69
	v_pk_add_f32 v[64:65], v[70:71], v[64:65]
	v_lshlrev_b64 v[66:67], 13, v[170:171]
	v_pk_fma_f32 v[64:65], v[64:65], s[18:19], v[166:167] op_sel_hi:[1,0,0]
	v_lshl_add_u64 v[66:67], s[10:11], 0, v[66:67]
	v_mul_f32_e32 v68, 0x4b800000, v65
	v_cmp_gt_f32_e32 vcc, s50, v65
	v_lshl_add_u64 v[66:67], v[66:67], 0, s[30:31]
	v_lshl_add_u64 v[66:67], v[66:67], 0, s[4:5]
	v_cndmask_b32_e32 v65, v65, v68, vcc
	v_rsq_f32_e32 v65, v65
;     __device__ __forceinline__ void operator()(const f32x4 (&acc)[2][2][4][2], const pg8::Unit& u, int wr, int wc, int fr, int fq) const {
;     ...
;         for (int ai = 0; ai < 2; ++ai)
; #pragma unroll
;             for (int m = 0; m < 4; ++m) {
;                 const int row = u.pm * 256 + ai * 128 + wr * 64 + m * 16 + fr;
;                 const float tot = (sq[ai][m].x + sq[ai][m].y) + (sq[ai][m].z + sq[ai][m].w);
;                 const float rn = rsqrtf(tot * (1.f / 1024.f) + EPS);
; #pragma unroll
;                 for (int bj = 0; bj < 2; ++bj) {
;                     float y[8];
; #pragma unroll
;                     for (int n = 0; n < 2; ++n)
; #pragma unroll
;                         for (int e = 0; e < 4; ++e) { const float h = fmaxf(acc[ai][bj][m][n][e] * rn, 0.f); y[n * 4 + e] = h * h; }
;                     store8(H + (size_t)row * FF + u.pn * 256 + 128 * bj + 32 * wc + 8 * fq, y);
;                 }
	v_lshl_add_u64 v[66:67], v[66:67], 0, v[152:153]
	v_mul_f32_e32 v68, 0x45800000, v65
	v_cndmask_b32_e32 v65, v65, v68, vcc
	v_mul_f32_e32 v56, v56, v65
	v_max_f32_e32 v56, 0, v56
	v_mul_f32_e32 v68, v56, v56
	v_mul_f32_e32 v56, v57, v65
	v_max_f32_e32 v56, 0, v56
	v_mul_f32_e32 v69, v56, v56
	v_mul_f32_e32 v56, v58, v65
	v_max_f32_e32 v56, 0, v56
	v_mul_f32_e32 v60, v60, v65
	v_mul_f32_e32 v61, v61, v65
	v_mul_f32_e32 v70, v56, v56
	v_mul_f32_e32 v56, v59, v65
	v_max_f32_e32 v60, 0, v60
	v_max_f32_e32 v61, 0, v61
	v_mul_f32_e32 v62, v62, v65
	v_mul_f32_e32 v63, v63, v65
	v_max_f32_e32 v56, 0, v56
	v_mul_f32_e32 v48, v48, v65
	v_mul_f32_e32 v60, v60, v60
	v_mul_f32_e32 v61, v61, v61
	v_max_f32_e32 v62, 0, v62
	v_max_f32_e32 v63, 0, v63
	v_mul_f32_e32 v59, v56, v56
	v_cvt_pk_bf16_f32 v56, v60, v61
	v_max_f32_e32 v48, 0, v48
	v_mul_f32_e32 v62, v62, v62
	v_mul_f32_e32 v63, v63, v63
	v_cvt_pk_bf16_f32 v57, v62, v63
	v_cvt_pk_bf16_f32 v58, v68, v69
	v_cvt_pk_bf16_f32 v59, v70, v59
	global_store_dwordx4 v[66:67], v[56:59], off nt
	v_mul_f32_e32 v52, v52, v65
	v_max_f32_e32 v52, 0, v52
	v_mul_f32_e32 v56, v48, v48
	v_mul_f32_e32 v48, v49, v65
	v_max_f32_e32 v48, 0, v48
	v_mul_f32_e32 v57, v48, v48
	v_mul_f32_e32 v48, v50, v65
	v_max_f32_e32 v48, 0, v48
	v_mul_f32_e32 v53, v53, v65
	v_mul_f32_e32 v58, v48, v48
	v_mul_f32_e32 v48, v51, v65
	v_mul_f32_e32 v50, 0x4b800000, v64
	v_cmp_gt_f32_e32 vcc, s50, v64
	v_mul_f32_e32 v52, v52, v52
	v_max_f32_e32 v53, 0, v53
	v_max_f32_e32 v48, 0, v48
	v_cndmask_b32_e32 v50, v64, v50, vcc
	v_mul_f32_e32 v53, v53, v53
	v_mul_f32_e32 v51, v48, v48
	v_cvt_pk_bf16_f32 v48, v52, v53
	v_rsq_f32_e32 v52, v50
	v_mul_f32_e32 v54, v54, v65
	v_mul_f32_e32 v55, v55, v65
	v_max_f32_e32 v54, 0, v54
	v_max_f32_e32 v55, 0, v55
	v_mul_f32_e32 v54, v54, v54
	v_mul_f32_e32 v55, v55, v55
	v_cvt_pk_bf16_f32 v49, v54, v55
	v_cvt_pk_bf16_f32 v50, v56, v57
	v_cvt_pk_bf16_f32 v51, v58, v51
	global_store_dwordx4 v[66:67], v[48:51], off offset:256 nt
	s_nop 1
	v_mul_f32_e32 v48, 0x45800000, v52
	v_cndmask_b32_e32 v50, v52, v48, vcc
	v_mul_f32_e32 v40, v40, v50
	v_max_f32_e32 v40, 0, v40
	v_mul_f32_e32 v53, v40, v40
	v_mul_f32_e32 v40, v41, v50
	v_mul_f32_e32 v44, v44, v50
	v_max_f32_e32 v40, 0, v40
	v_max_f32_e32 v44, 0, v44
	v_mul_f32_e32 v54, v40, v40
	v_mul_f32_e32 v40, v42, v50
	v_mul_f32_e32 v51, v44, v44
	v_mul_f32_e32 v44, v45, v50
	v_max_f32_e32 v40, 0, v40
	v_max_f32_e32 v44, 0, v44
	v_mul_f32_e32 v55, v40, v40
	v_mul_f32_e32 v40, v43, v50
	v_lshlrev_b64 v[48:49], 13, v[168:169]
	v_mul_f32_e32 v52, v44, v44
	v_mul_f32_e32 v44, v46, v50
	v_max_f32_e32 v40, 0, v40
	v_max_f32_e32 v44, 0, v44
	v_mul_f32_e32 v43, v40, v40
	v_lshl_add_u64 v[40:41], s[10:11], 0, v[48:49]
	v_mul_f32_e32 v46, v44, v44
	v_mul_f32_e32 v44, v47, v50
	v_lshl_add_u64 v[40:41], v[40:41], 0, s[30:31]
	v_max_f32_e32 v44, 0, v44
	v_lshl_add_u64 v[40:41], v[40:41], 0, s[4:5]
	v_mul_f32_e32 v32, v32, v50
	v_mul_f32_e32 v47, v44, v44
	v_lshl_add_u64 v[44:45], v[40:41], 0, v[152:153]
	v_cvt_pk_bf16_f32 v40, v51, v52
	v_max_f32_e32 v32, 0, v32
	v_cvt_pk_bf16_f32 v41, v46, v47
	v_cvt_pk_bf16_f32 v42, v53, v54
	v_cvt_pk_bf16_f32 v43, v55, v43
	global_store_dwordx4 v[44:45], v[40:43], off nt
	v_mul_f32_e32 v36, v36, v50
	v_mul_f32_e32 v37, v37, v50
	v_mul_f32_e32 v40, v32, v32
	v_mul_f32_e32 v32, v33, v50
	v_max_f32_e32 v32, 0, v32
	v_mul_f32_e32 v41, v32, v32
	v_mul_f32_e32 v32, v34, v50
	v_max_f32_e32 v32, 0, v32
	v_mul_f32_e32 v38, v38, v50
	v_mul_f32_e32 v39, v39, v50
	v_mul_f32_e32 v42, v32, v32
	v_mul_f32_e32 v32, v35, v50
	v_max_f32_e32 v36, 0, v36
	v_max_f32_e32 v37, 0, v37
	v_max_f32_e32 v38, 0, v38
	v_max_f32_e32 v39, 0, v39
	v_max_f32_e32 v32, 0, v32
	v_mul_f32_e32 v36, v36, v36
	v_mul_f32_e32 v37, v37, v37
	v_mul_f32_e32 v38, v38, v38
	v_mul_f32_e32 v39, v39, v39
	v_mul_f32_e32 v35, v32, v32
	v_cvt_pk_bf16_f32 v32, v36, v37
	v_cvt_pk_bf16_f32 v33, v38, v39
	v_cvt_pk_bf16_f32 v34, v40, v41
	v_cvt_pk_bf16_f32 v35, v42, v35
	global_store_dwordx4 v[44:45], v[32:35], off offset:256 nt
	v_mov_b32_e32 v36, v129
	v_mov_b32_e32 v37, v130
	v_mov_b32_e32 v32, v133
	v_mov_b32_e32 v33, v134
	v_mov_b32_e32 v133, v135
	v_mov_b32_e32 v129, v131
	v_pk_add_f32 v[32:33], v[32:33], v[132:133]
	v_pk_add_f32 v[36:37], v[36:37], v[128:129]
	v_mov_b32_e32 v39, v32
	v_mov_b32_e32 v38, v36
	v_mov_b32_e32 v32, v37
	v_pk_add_f32 v[32:33], v[38:39], v[32:33]
	v_lshlrev_b64 v[34:35], 13, v[164:165]
; template <class Epi, class Sched, bool ALIGN_EPI = false, bool SP2 = false>
; __device__ __forceinline__ void gemm_phase(PG8_LAS unsigned char* lds, const Gemm g, const Sched& S, const Epi& E) {
;     ...
;         if (!has_next) break;
; #pragma unroll
;         for (int a = 0; a < 2; ++a)
; #pragma unroll
;             for (int b = 0; b < 2; ++b)
; #pragma unroll
;                 for (int m = 0; m < 4; ++m)
; #pragma unroll
;                     for (int n = 0; n < 2; ++n) acc[a][b][m][n] = (f32x4){0.f, 0.f, 0.f, 0.f};
;         cur = nxt; cA = nA; cB = nB; ++ui;
;     __device__ __forceinline__ void operator()(const f32x4 (&acc)[2][2][4][2], const pg8::Unit& u, int wr, int wc, int fr, int fq) const {
;     ...
;         for (int ai = 0; ai < 2; ++ai)
; #pragma unroll
;             for (int m = 0; m < 4; ++m) {
;                 const int row = u.pm * 256 + ai * 128 + wr * 64 + m * 16 + fr;
;                 const float tot = (sq[ai][m].x + sq[ai][m].y) + (sq[ai][m].z + sq[ai][m].w);
;                 const float rn = rsqrtf(tot * (1.f / 1024.f) + EPS);
; #pragma unroll
;                 for (int bj = 0; bj < 2; ++bj) {
;                     float y[8];
; #pragma unroll
;                     for (int n = 0; n < 2; ++n)
; #pragma unroll
;                         for (int e = 0; e < 4; ++e) { const float h = fmaxf(acc[ai][bj][m][n][e] * rn, 0.f); y[n * 4 + e] = h * h; }
;                     store8(H + (size_t)row * FF + u.pn * 256 + 128 * bj + 32 * wc + 8 * fq, y);
;                 }
	v_pk_fma_f32 v[32:33], v[32:33], s[18:19], v[166:167] op_sel_hi:[1,0,0]
	v_lshl_add_u64 v[34:35], s[10:11], 0, v[34:35]
	v_mul_f32_e32 v36, 0x4b800000, v33
	v_cmp_gt_f32_e32 vcc, s50, v33
	v_lshl_add_u64 v[34:35], v[34:35], 0, s[30:31]
	v_lshl_add_u64 v[34:35], v[34:35], 0, s[4:5]
	v_cndmask_b32_e32 v33, v33, v36, vcc
	v_rsq_f32_e32 v33, v33
	v_lshl_add_u64 v[34:35], v[34:35], 0, v[152:153]
	v_mul_f32_e32 v36, 0x45800000, v33
	v_cndmask_b32_e32 v33, v33, v36, vcc
	v_mul_f32_e32 v24, v24, v33
	v_max_f32_e32 v24, 0, v24
	v_mul_f32_e32 v36, v24, v24
	v_mul_f32_e32 v24, v25, v33
	v_max_f32_e32 v24, 0, v24
	v_mul_f32_e32 v37, v24, v24
	v_mul_f32_e32 v24, v26, v33
	v_max_f32_e32 v24, 0, v24
	v_mul_f32_e32 v28, v28, v33
	v_mul_f32_e32 v29, v29, v33
	v_mul_f32_e32 v38, v24, v24
	v_mul_f32_e32 v24, v27, v33
	v_max_f32_e32 v28, 0, v28
	v_max_f32_e32 v29, 0, v29
	v_mul_f32_e32 v30, v30, v33
	v_mul_f32_e32 v31, v31, v33
	v_max_f32_e32 v24, 0, v24
	v_mul_f32_e32 v16, v16, v33
	v_mul_f32_e32 v28, v28, v28
	v_mul_f32_e32 v29, v29, v29
	v_max_f32_e32 v30, 0, v30
	v_max_f32_e32 v31, 0, v31
	v_mul_f32_e32 v27, v24, v24
	v_cvt_pk_bf16_f32 v24, v28, v29
	v_max_f32_e32 v16, 0, v16
	v_mul_f32_e32 v30, v30, v30
	v_mul_f32_e32 v31, v31, v31
	v_cvt_pk_bf16_f32 v25, v30, v31
	v_cvt_pk_bf16_f32 v26, v36, v37
	v_cvt_pk_bf16_f32 v27, v38, v27
	global_store_dwordx4 v[34:35], v[24:27], off nt
	v_mul_f32_e32 v20, v20, v33
	v_max_f32_e32 v20, 0, v20
	v_mul_f32_e32 v24, v16, v16
	v_mul_f32_e32 v16, v17, v33
	v_max_f32_e32 v16, 0, v16
	v_mul_f32_e32 v25, v16, v16
	v_mul_f32_e32 v16, v18, v33
	v_max_f32_e32 v16, 0, v16
	v_mul_f32_e32 v21, v21, v33
	v_mul_f32_e32 v26, v16, v16
	v_mul_f32_e32 v16, v19, v33
	v_mul_f32_e32 v18, 0x4b800000, v32
	v_cmp_gt_f32_e32 vcc, s50, v32
	v_mul_f32_e32 v20, v20, v20
	v_max_f32_e32 v21, 0, v21
	v_max_f32_e32 v16, 0, v16
	v_cndmask_b32_e32 v18, v32, v18, vcc
	v_mul_f32_e32 v21, v21, v21
	v_mul_f32_e32 v19, v16, v16
	v_cvt_pk_bf16_f32 v16, v20, v21
	v_rsq_f32_e32 v20, v18
	v_mul_f32_e32 v22, v22, v33
	v_mul_f32_e32 v23, v23, v33
	v_max_f32_e32 v22, 0, v22
	v_max_f32_e32 v23, 0, v23
	v_mul_f32_e32 v22, v22, v22
	v_mul_f32_e32 v23, v23, v23
	v_cvt_pk_bf16_f32 v17, v22, v23
	v_cvt_pk_bf16_f32 v18, v24, v25
	v_cvt_pk_bf16_f32 v19, v26, v19
	global_store_dwordx4 v[34:35], v[16:19], off offset:256 nt
	s_nop 1
	v_mul_f32_e32 v16, 0x45800000, v20
	v_cndmask_b32_e32 v18, v20, v16, vcc
	v_mul_f32_e32 v8, v8, v18
	v_max_f32_e32 v8, 0, v8
	v_mul_f32_e32 v21, v8, v8
	v_mul_f32_e32 v8, v9, v18
	v_mul_f32_e32 v12, v12, v18
	v_max_f32_e32 v8, 0, v8
	v_max_f32_e32 v12, 0, v12
	v_mul_f32_e32 v22, v8, v8
	v_mul_f32_e32 v8, v10, v18
	v_mul_f32_e32 v19, v12, v12
	v_mul_f32_e32 v12, v13, v18
	v_max_f32_e32 v8, 0, v8
	v_max_f32_e32 v12, 0, v12
	v_mul_f32_e32 v23, v8, v8
	v_mul_f32_e32 v8, v11, v18
	v_lshlrev_b64 v[16:17], 13, v[162:163]
	v_mul_f32_e32 v20, v12, v12
	v_mul_f32_e32 v12, v14, v18
	v_max_f32_e32 v8, 0, v8
	v_max_f32_e32 v12, 0, v12
	v_mul_f32_e32 v11, v8, v8
	v_lshl_add_u64 v[8:9], s[10:11], 0, v[16:17]
	v_mul_f32_e32 v14, v12, v12
	v_mul_f32_e32 v12, v15, v18
	v_lshl_add_u64 v[8:9], v[8:9], 0, s[30:31]
	v_max_f32_e32 v12, 0, v12
	v_lshl_add_u64 v[8:9], v[8:9], 0, s[4:5]
	v_mul_f32_e32 v0, v0, v18
	v_mul_f32_e32 v15, v12, v12
	v_lshl_add_u64 v[12:13], v[8:9], 0, v[152:153]
	v_cvt_pk_bf16_f32 v8, v19, v20
	v_max_f32_e32 v0, 0, v0
	v_cvt_pk_bf16_f32 v9, v14, v15
	v_cvt_pk_bf16_f32 v10, v21, v22
	v_cvt_pk_bf16_f32 v11, v23, v11
	global_store_dwordx4 v[12:13], v[8:11], off nt
	v_mul_f32_e32 v4, v4, v18
	v_mul_f32_e32 v5, v5, v18
	v_mul_f32_e32 v8, v0, v0
	v_mul_f32_e32 v0, v1, v18
	v_max_f32_e32 v0, 0, v0
	v_mul_f32_e32 v9, v0, v0
	v_mul_f32_e32 v0, v2, v18
	v_max_f32_e32 v0, 0, v0
	v_mul_f32_e32 v10, v0, v0
	v_mul_f32_e32 v0, v3, v18
	v_mul_f32_e32 v6, v6, v18
	v_mul_f32_e32 v7, v7, v18
	v_max_f32_e32 v0, 0, v0
	v_max_f32_e32 v4, 0, v4
	v_max_f32_e32 v5, 0, v5
	v_max_f32_e32 v6, 0, v6
	v_max_f32_e32 v7, 0, v7
	v_mul_f32_e32 v3, v0, v0
	s_andn2_b64 vcc, exec, s[2:3]
	s_mov_b64 s[2:3], -1
	v_mul_f32_e32 v4, v4, v4
	v_mul_f32_e32 v5, v5, v5
	v_mul_f32_e32 v6, v6, v6
	v_mul_f32_e32 v7, v7, v7
	v_cvt_pk_bf16_f32 v0, v4, v5
	v_cvt_pk_bf16_f32 v1, v6, v7
	v_cvt_pk_bf16_f32 v2, v8, v9
	v_cvt_pk_bf16_f32 v3, v10, v3
	global_store_dwordx4 v[12:13], v[0:3], off offset:256 nt
	s_cbranch_vccnz .LBB0_999
	s_andn2_b64 vcc, exec, s[6:7]
	s_cbranch_vccnz .LBB0_998
	s_barrier
	s_branch .LBB0_998
